# adaLN modulation GEMV k-loop: 98 serial load-wait round trips replaced by 14 groups of 7 rows with two groups of loads in flight
# speedup vs baseline: 1.0010x; 1.0010x over previous
; __device__ __forceinline__ void adaln_unit(KP p, int u, float* sm, int tid) {
;   const int l = u >> 7, j0 = (u & 127) * 96;
;   const float* c = p->in[1]; const float* cc = p->in[3];
;   for (int k = tid; k < DM; k += NTH) { const float a = c[k]; sm[k] = a / (1.0f + expf(-a)); const float b = cc[k]; sm[DM + k] = b / (1.0f + expf(-b)); }
;   __syncthreads();
;   const int c4 = tid % 24, rg = tid / 24;
;   float* red = sm + 2 * DM;
;   if (rg < 21) {
;     f32x4 a1 = (f32x4){0.f, 0.f, 0.f, 0.f}, a2 = a1;
;     const float* W = p->in[6] + (size_t)l * DM * 12288 + j0 + 4 * c4;
;     for (int k = rg; k < DM; k += 21) { const f32x4 w = *(const f32x4*)(W + (size_t)k * 12288); a1 += sm[k] * w; a2 += sm[DM + k] * w; }
.LBB0_502:
	s_or_b64 exec, exec, s[28:29]
	s_ashr_i32 s20, s33, 7
	s_waitcnt lgkmcnt(0)
	s_barrier
	s_and_saveexec_b64 s[16:17], s[8:9]
	s_cbranch_execz .LBB0_506
	v_readlane_b32 s18, v254, 9
	v_readlane_b32 s19, v254, 10
	s_load_dwordx2 s[18:19], s[18:19], 0x30
	s_and_b32 s21, s26, 0x7f
	s_mul_i32 s28, s20, 0x6000000
	s_mulk_i32 s21, 0x180
	s_mul_hi_i32 s29, s20, 0x6000000
	s_waitcnt lgkmcnt(0)
	v_lshl_add_u64 v[0:1], s[18:19], 0, v[8:9]
	s_or_b32 s28, s28, s21
	v_lshl_add_u64 v[10:11], v[0:1], 0, s[28:29]
	v_mov_b32_e32 v0, 0
	s_mov_b64 s[18:19], 0
	v_mov_b32_e32 v12, v32
	v_mov_b32_e32 v13, v31
	v_mov_b32_e32 v1, v0
	v_mov_b32_e32 v2, v0
	v_mov_b32_e32 v3, v0
	v_mov_b32_e32 v4, v0
	v_mov_b32_e32 v5, v0
	v_mov_b32_e32 v6, v0
	v_mov_b32_e32 v7, v0
	s_mov_b64 s[28:29], 0xfc000
	v_cmp_gt_i32_e32 vcc, -10, v13
	s_nop 1
	v_mov_b32_e32 v125, 0
	v_mov_b32_e32 v124, 0xfc000
	v_cndmask_b32_e32 v124, 0, v124, vcc
	global_load_dwordx4 v[40:43], v[10:11], off
	ds_read2st64_b32 v[96:97], v12 offset1:32
	v_add_u32_e32 v12, 0x54, v12
	v_lshl_add_u64 v[10:11], v[10:11], 0, s[28:29]
	global_load_dwordx4 v[44:47], v[10:11], off
	ds_read2st64_b32 v[98:99], v12 offset1:32
	v_add_u32_e32 v12, 0x54, v12
	v_lshl_add_u64 v[10:11], v[10:11], 0, s[28:29]
	global_load_dwordx4 v[48:51], v[10:11], off
	ds_read2st64_b32 v[100:101], v12 offset1:32
	v_add_u32_e32 v12, 0x54, v12
	v_lshl_add_u64 v[10:11], v[10:11], 0, s[28:29]
	global_load_dwordx4 v[52:55], v[10:11], off
	ds_read2st64_b32 v[102:103], v12 offset1:32
	v_add_u32_e32 v12, 0x54, v12
	v_lshl_add_u64 v[10:11], v[10:11], 0, s[28:29]
	global_load_dwordx4 v[56:59], v[10:11], off
	ds_read2st64_b32 v[104:105], v12 offset1:32
	v_add_u32_e32 v12, 0x54, v12
	v_lshl_add_u64 v[10:11], v[10:11], 0, s[28:29]
	global_load_dwordx4 v[60:63], v[10:11], off
	ds_read2st64_b32 v[106:107], v12 offset1:32
	v_add_u32_e32 v12, 0x54, v12
	v_lshl_add_u64 v[10:11], v[10:11], 0, s[28:29]
	global_load_dwordx4 v[64:67], v[10:11], off
	ds_read2st64_b32 v[108:109], v12 offset1:32
	v_add_u32_e32 v12, 0x54, v12
	v_lshl_add_u64 v[10:11], v[10:11], 0, s[28:29]
	global_load_dwordx4 v[68:71], v[10:11], off
	ds_read2st64_b32 v[110:111], v12 offset1:32
	v_add_u32_e32 v12, 0x54, v12
	v_lshl_add_u64 v[10:11], v[10:11], 0, s[28:29]
	global_load_dwordx4 v[72:75], v[10:11], off
	ds_read2st64_b32 v[112:113], v12 offset1:32
	v_add_u32_e32 v12, 0x54, v12
	v_lshl_add_u64 v[10:11], v[10:11], 0, s[28:29]
	global_load_dwordx4 v[76:79], v[10:11], off
	ds_read2st64_b32 v[114:115], v12 offset1:32
	v_add_u32_e32 v12, 0x54, v12
	v_lshl_add_u64 v[10:11], v[10:11], 0, s[28:29]
	global_load_dwordx4 v[80:83], v[10:11], off
	ds_read2st64_b32 v[116:117], v12 offset1:32
	v_add_u32_e32 v12, 0x54, v12
	v_lshl_add_u64 v[10:11], v[10:11], 0, s[28:29]
	global_load_dwordx4 v[84:87], v[10:11], off
	ds_read2st64_b32 v[118:119], v12 offset1:32
	v_add_u32_e32 v12, 0x54, v12
	v_lshl_add_u64 v[10:11], v[10:11], 0, s[28:29]
	global_load_dwordx4 v[88:91], v[10:11], off
	ds_read2st64_b32 v[120:121], v12 offset1:32
	v_add_u32_e32 v12, 0x54, v12
	v_lshl_add_u64 v[10:11], v[10:11], 0, s[28:29]
	global_load_dwordx4 v[92:95], v[10:11], off
	ds_read2st64_b32 v[122:123], v12 offset1:32
	v_add_u32_e32 v12, 0x54, v12
	v_lshl_add_u64 v[10:11], v[10:11], 0, s[28:29]
	s_waitcnt vmcnt(7) lgkmcnt(7)
	v_pk_fma_f32 v[2:3], v[42:43], v[96:97], v[2:3] op_sel_hi:[1,0,1]
	v_pk_fma_f32 v[0:1], v[40:41], v[96:97], v[0:1] op_sel_hi:[1,0,1]
	v_pk_fma_f32 v[6:7], v[42:43], v[96:97], v[6:7] op_sel:[0,1,0] op_sel_hi:[1,1,1]
	v_pk_fma_f32 v[4:5], v[40:41], v[96:97], v[4:5] op_sel:[0,1,0] op_sel_hi:[1,1,1]
	v_pk_fma_f32 v[2:3], v[46:47], v[98:99], v[2:3] op_sel_hi:[1,0,1]
	v_pk_fma_f32 v[0:1], v[44:45], v[98:99], v[0:1] op_sel_hi:[1,0,1]
	v_pk_fma_f32 v[6:7], v[46:47], v[98:99], v[6:7] op_sel:[0,1,0] op_sel_hi:[1,1,1]
	v_pk_fma_f32 v[4:5], v[44:45], v[98:99], v[4:5] op_sel:[0,1,0] op_sel_hi:[1,1,1]
	v_pk_fma_f32 v[2:3], v[50:51], v[100:101], v[2:3] op_sel_hi:[1,0,1]
	v_pk_fma_f32 v[0:1], v[48:49], v[100:101], v[0:1] op_sel_hi:[1,0,1]
	v_pk_fma_f32 v[6:7], v[50:51], v[100:101], v[6:7] op_sel:[0,1,0] op_sel_hi:[1,1,1]
	v_pk_fma_f32 v[4:5], v[48:49], v[100:101], v[4:5] op_sel:[0,1,0] op_sel_hi:[1,1,1]
	v_pk_fma_f32 v[2:3], v[54:55], v[102:103], v[2:3] op_sel_hi:[1,0,1]
	v_pk_fma_f32 v[0:1], v[52:53], v[102:103], v[0:1] op_sel_hi:[1,0,1]
	v_pk_fma_f32 v[6:7], v[54:55], v[102:103], v[6:7] op_sel:[0,1,0] op_sel_hi:[1,1,1]
	v_pk_fma_f32 v[4:5], v[52:53], v[102:103], v[4:5] op_sel:[0,1,0] op_sel_hi:[1,1,1]
	v_pk_fma_f32 v[2:3], v[58:59], v[104:105], v[2:3] op_sel_hi:[1,0,1]
	v_pk_fma_f32 v[0:1], v[56:57], v[104:105], v[0:1] op_sel_hi:[1,0,1]
	v_pk_fma_f32 v[6:7], v[58:59], v[104:105], v[6:7] op_sel:[0,1,0] op_sel_hi:[1,1,1]
	v_pk_fma_f32 v[4:5], v[56:57], v[104:105], v[4:5] op_sel:[0,1,0] op_sel_hi:[1,1,1]
	v_pk_fma_f32 v[2:3], v[62:63], v[106:107], v[2:3] op_sel_hi:[1,0,1]
	v_pk_fma_f32 v[0:1], v[60:61], v[106:107], v[0:1] op_sel_hi:[1,0,1]
	v_pk_fma_f32 v[6:7], v[62:63], v[106:107], v[6:7] op_sel:[0,1,0] op_sel_hi:[1,1,1]
	v_pk_fma_f32 v[4:5], v[60:61], v[106:107], v[4:5] op_sel:[0,1,0] op_sel_hi:[1,1,1]
	v_pk_fma_f32 v[2:3], v[66:67], v[108:109], v[2:3] op_sel_hi:[1,0,1]
	v_pk_fma_f32 v[0:1], v[64:65], v[108:109], v[0:1] op_sel_hi:[1,0,1]
	v_pk_fma_f32 v[6:7], v[66:67], v[108:109], v[6:7] op_sel:[0,1,0] op_sel_hi:[1,1,1]
	v_pk_fma_f32 v[4:5], v[64:65], v[108:109], v[4:5] op_sel:[0,1,0] op_sel_hi:[1,1,1]
	global_load_dwordx4 v[40:43], v[10:11], off
	ds_read2st64_b32 v[96:97], v12 offset1:32
	v_add_u32_e32 v12, 0x54, v12
	v_lshl_add_u64 v[10:11], v[10:11], 0, s[28:29]
	global_load_dwordx4 v[44:47], v[10:11], off
	ds_read2st64_b32 v[98:99], v12 offset1:32
	v_add_u32_e32 v12, 0x54, v12
	v_lshl_add_u64 v[10:11], v[10:11], 0, s[28:29]
	global_load_dwordx4 v[48:51], v[10:11], off
	ds_read2st64_b32 v[100:101], v12 offset1:32
	v_add_u32_e32 v12, 0x54, v12
	v_lshl_add_u64 v[10:11], v[10:11], 0, s[28:29]
	global_load_dwordx4 v[52:55], v[10:11], off
	ds_read2st64_b32 v[102:103], v12 offset1:32
	v_add_u32_e32 v12, 0x54, v12
	v_lshl_add_u64 v[10:11], v[10:11], 0, s[28:29]
	global_load_dwordx4 v[56:59], v[10:11], off
	ds_read2st64_b32 v[104:105], v12 offset1:32
	v_add_u32_e32 v12, 0x54, v12
	v_lshl_add_u64 v[10:11], v[10:11], 0, s[28:29]
	global_load_dwordx4 v[60:63], v[10:11], off
	ds_read2st64_b32 v[106:107], v12 offset1:32
	v_add_u32_e32 v12, 0x54, v12
	v_lshl_add_u64 v[10:11], v[10:11], 0, s[28:29]
	global_load_dwordx4 v[64:67], v[10:11], off
	ds_read2st64_b32 v[108:109], v12 offset1:32
	v_add_u32_e32 v12, 0x54, v12
	v_lshl_add_u64 v[10:11], v[10:11], 0, s[28:29]
	s_waitcnt vmcnt(7) lgkmcnt(7)
; __device__ __forceinline__ void adaln_unit(KP p, int u, float* sm, int tid) {
;     ...
;     for (int k = rg; k < DM; k += 21) { const f32x4 w = *(const f32x4*)(W + (size_t)k * 12288); a1 += sm[k] * w; a2 += sm[DM + k] * w; }
	v_pk_fma_f32 v[2:3], v[70:71], v[110:111], v[2:3] op_sel_hi:[1,0,1]
	v_pk_fma_f32 v[0:1], v[68:69], v[110:111], v[0:1] op_sel_hi:[1,0,1]
	v_pk_fma_f32 v[6:7], v[70:71], v[110:111], v[6:7] op_sel:[0,1,0] op_sel_hi:[1,1,1]
	v_pk_fma_f32 v[4:5], v[68:69], v[110:111], v[4:5] op_sel:[0,1,0] op_sel_hi:[1,1,1]
	v_pk_fma_f32 v[2:3], v[74:75], v[112:113], v[2:3] op_sel_hi:[1,0,1]
	v_pk_fma_f32 v[0:1], v[72:73], v[112:113], v[0:1] op_sel_hi:[1,0,1]
	v_pk_fma_f32 v[6:7], v[74:75], v[112:113], v[6:7] op_sel:[0,1,0] op_sel_hi:[1,1,1]
	v_pk_fma_f32 v[4:5], v[72:73], v[112:113], v[4:5] op_sel:[0,1,0] op_sel_hi:[1,1,1]
	v_pk_fma_f32 v[2:3], v[78:79], v[114:115], v[2:3] op_sel_hi:[1,0,1]
	v_pk_fma_f32 v[0:1], v[76:77], v[114:115], v[0:1] op_sel_hi:[1,0,1]
	v_pk_fma_f32 v[6:7], v[78:79], v[114:115], v[6:7] op_sel:[0,1,0] op_sel_hi:[1,1,1]
	v_pk_fma_f32 v[4:5], v[76:77], v[114:115], v[4:5] op_sel:[0,1,0] op_sel_hi:[1,1,1]
	v_pk_fma_f32 v[2:3], v[82:83], v[116:117], v[2:3] op_sel_hi:[1,0,1]
	v_pk_fma_f32 v[0:1], v[80:81], v[116:117], v[0:1] op_sel_hi:[1,0,1]
	v_pk_fma_f32 v[6:7], v[82:83], v[116:117], v[6:7] op_sel:[0,1,0] op_sel_hi:[1,1,1]
	v_pk_fma_f32 v[4:5], v[80:81], v[116:117], v[4:5] op_sel:[0,1,0] op_sel_hi:[1,1,1]
	v_pk_fma_f32 v[2:3], v[86:87], v[118:119], v[2:3] op_sel_hi:[1,0,1]
	v_pk_fma_f32 v[0:1], v[84:85], v[118:119], v[0:1] op_sel_hi:[1,0,1]
	v_pk_fma_f32 v[6:7], v[86:87], v[118:119], v[6:7] op_sel:[0,1,0] op_sel_hi:[1,1,1]
	v_pk_fma_f32 v[4:5], v[84:85], v[118:119], v[4:5] op_sel:[0,1,0] op_sel_hi:[1,1,1]
	v_pk_fma_f32 v[2:3], v[90:91], v[120:121], v[2:3] op_sel_hi:[1,0,1]
	v_pk_fma_f32 v[0:1], v[88:89], v[120:121], v[0:1] op_sel_hi:[1,0,1]
	v_pk_fma_f32 v[6:7], v[90:91], v[120:121], v[6:7] op_sel:[0,1,0] op_sel_hi:[1,1,1]
	v_pk_fma_f32 v[4:5], v[88:89], v[120:121], v[4:5] op_sel:[0,1,0] op_sel_hi:[1,1,1]
	v_pk_fma_f32 v[2:3], v[94:95], v[122:123], v[2:3] op_sel_hi:[1,0,1]
	v_pk_fma_f32 v[0:1], v[92:93], v[122:123], v[0:1] op_sel_hi:[1,0,1]
	v_pk_fma_f32 v[6:7], v[94:95], v[122:123], v[6:7] op_sel:[0,1,0] op_sel_hi:[1,1,1]
	v_pk_fma_f32 v[4:5], v[92:93], v[122:123], v[4:5] op_sel:[0,1,0] op_sel_hi:[1,1,1]
	global_load_dwordx4 v[68:71], v[10:11], off
	ds_read2st64_b32 v[110:111], v12 offset1:32
	v_add_u32_e32 v12, 0x54, v12
	v_lshl_add_u64 v[10:11], v[10:11], 0, s[28:29]
	global_load_dwordx4 v[72:75], v[10:11], off
	ds_read2st64_b32 v[112:113], v12 offset1:32
	v_add_u32_e32 v12, 0x54, v12
	v_lshl_add_u64 v[10:11], v[10:11], 0, s[28:29]
	global_load_dwordx4 v[76:79], v[10:11], off
	ds_read2st64_b32 v[114:115], v12 offset1:32
	v_add_u32_e32 v12, 0x54, v12
	v_lshl_add_u64 v[10:11], v[10:11], 0, s[28:29]
	global_load_dwordx4 v[80:83], v[10:11], off
	ds_read2st64_b32 v[116:117], v12 offset1:32
	v_add_u32_e32 v12, 0x54, v12
	v_lshl_add_u64 v[10:11], v[10:11], 0, s[28:29]
	global_load_dwordx4 v[84:87], v[10:11], off
	ds_read2st64_b32 v[118:119], v12 offset1:32
	v_add_u32_e32 v12, 0x54, v12
	v_lshl_add_u64 v[10:11], v[10:11], 0, s[28:29]
	global_load_dwordx4 v[88:91], v[10:11], off
	ds_read2st64_b32 v[120:121], v12 offset1:32
	v_add_u32_e32 v12, 0x54, v12
	v_lshl_add_u64 v[10:11], v[10:11], 0, s[28:29]
	global_load_dwordx4 v[92:95], v[10:11], off
	ds_read2st64_b32 v[122:123], v12 offset1:32
	v_add_u32_e32 v12, 0x54, v12
	v_lshl_add_u64 v[10:11], v[10:11], 0, s[28:29]
	s_waitcnt vmcnt(7) lgkmcnt(7)
	v_pk_fma_f32 v[2:3], v[42:43], v[96:97], v[2:3] op_sel_hi:[1,0,1]
	v_pk_fma_f32 v[0:1], v[40:41], v[96:97], v[0:1] op_sel_hi:[1,0,1]
	v_pk_fma_f32 v[6:7], v[42:43], v[96:97], v[6:7] op_sel:[0,1,0] op_sel_hi:[1,1,1]
	v_pk_fma_f32 v[4:5], v[40:41], v[96:97], v[4:5] op_sel:[0,1,0] op_sel_hi:[1,1,1]
	v_pk_fma_f32 v[2:3], v[46:47], v[98:99], v[2:3] op_sel_hi:[1,0,1]
	v_pk_fma_f32 v[0:1], v[44:45], v[98:99], v[0:1] op_sel_hi:[1,0,1]
	v_pk_fma_f32 v[6:7], v[46:47], v[98:99], v[6:7] op_sel:[0,1,0] op_sel_hi:[1,1,1]
	v_pk_fma_f32 v[4:5], v[44:45], v[98:99], v[4:5] op_sel:[0,1,0] op_sel_hi:[1,1,1]
	v_pk_fma_f32 v[2:3], v[50:51], v[100:101], v[2:3] op_sel_hi:[1,0,1]
	v_pk_fma_f32 v[0:1], v[48:49], v[100:101], v[0:1] op_sel_hi:[1,0,1]
	v_pk_fma_f32 v[6:7], v[50:51], v[100:101], v[6:7] op_sel:[0,1,0] op_sel_hi:[1,1,1]
	v_pk_fma_f32 v[4:5], v[48:49], v[100:101], v[4:5] op_sel:[0,1,0] op_sel_hi:[1,1,1]
	v_pk_fma_f32 v[2:3], v[54:55], v[102:103], v[2:3] op_sel_hi:[1,0,1]
	v_pk_fma_f32 v[0:1], v[52:53], v[102:103], v[0:1] op_sel_hi:[1,0,1]
	v_pk_fma_f32 v[6:7], v[54:55], v[102:103], v[6:7] op_sel:[0,1,0] op_sel_hi:[1,1,1]
	v_pk_fma_f32 v[4:5], v[52:53], v[102:103], v[4:5] op_sel:[0,1,0] op_sel_hi:[1,1,1]
	v_pk_fma_f32 v[2:3], v[58:59], v[104:105], v[2:3] op_sel_hi:[1,0,1]
	v_pk_fma_f32 v[0:1], v[56:57], v[104:105], v[0:1] op_sel_hi:[1,0,1]
	v_pk_fma_f32 v[6:7], v[58:59], v[104:105], v[6:7] op_sel:[0,1,0] op_sel_hi:[1,1,1]
	v_pk_fma_f32 v[4:5], v[56:57], v[104:105], v[4:5] op_sel:[0,1,0] op_sel_hi:[1,1,1]
	v_pk_fma_f32 v[2:3], v[62:63], v[106:107], v[2:3] op_sel_hi:[1,0,1]
	v_pk_fma_f32 v[0:1], v[60:61], v[106:107], v[0:1] op_sel_hi:[1,0,1]
	v_pk_fma_f32 v[6:7], v[62:63], v[106:107], v[6:7] op_sel:[0,1,0] op_sel_hi:[1,1,1]
	v_pk_fma_f32 v[4:5], v[60:61], v[106:107], v[4:5] op_sel:[0,1,0] op_sel_hi:[1,1,1]
	v_pk_fma_f32 v[2:3], v[66:67], v[108:109], v[2:3] op_sel_hi:[1,0,1]
	v_pk_fma_f32 v[0:1], v[64:65], v[108:109], v[0:1] op_sel_hi:[1,0,1]
	v_pk_fma_f32 v[6:7], v[66:67], v[108:109], v[6:7] op_sel:[0,1,0] op_sel_hi:[1,1,1]
	v_pk_fma_f32 v[4:5], v[64:65], v[108:109], v[4:5] op_sel:[0,1,0] op_sel_hi:[1,1,1]
	global_load_dwordx4 v[40:43], v[10:11], off
	ds_read2st64_b32 v[96:97], v12 offset1:32
	v_add_u32_e32 v12, 0x54, v12
	v_lshl_add_u64 v[10:11], v[10:11], 0, s[28:29]
	global_load_dwordx4 v[44:47], v[10:11], off
	ds_read2st64_b32 v[98:99], v12 offset1:32
	v_add_u32_e32 v12, 0x54, v12
	v_lshl_add_u64 v[10:11], v[10:11], 0, s[28:29]
	global_load_dwordx4 v[48:51], v[10:11], off
	ds_read2st64_b32 v[100:101], v12 offset1:32
	v_add_u32_e32 v12, 0x54, v12
	v_lshl_add_u64 v[10:11], v[10:11], 0, s[28:29]
	global_load_dwordx4 v[52:55], v[10:11], off
	ds_read2st64_b32 v[102:103], v12 offset1:32
	v_add_u32_e32 v12, 0x54, v12
	v_lshl_add_u64 v[10:11], v[10:11], 0, s[28:29]
	global_load_dwordx4 v[56:59], v[10:11], off
	ds_read2st64_b32 v[104:105], v12 offset1:32
	v_add_u32_e32 v12, 0x54, v12
	v_lshl_add_u64 v[10:11], v[10:11], 0, s[28:29]
	global_load_dwordx4 v[60:63], v[10:11], off
	ds_read2st64_b32 v[106:107], v12 offset1:32
	v_add_u32_e32 v12, 0x54, v12
	v_lshl_add_u64 v[10:11], v[10:11], 0, s[28:29]
	global_load_dwordx4 v[64:67], v[10:11], off
	ds_read2st64_b32 v[108:109], v12 offset1:32
	v_add_u32_e32 v12, 0x54, v12
	v_lshl_add_u64 v[10:11], v[10:11], 0, s[28:29]
	s_waitcnt vmcnt(7) lgkmcnt(7)
; __device__ __forceinline__ void adaln_unit(KP p, int u, float* sm, int tid) {
;     ...
;     for (int k = rg; k < DM; k += 21) { const f32x4 w = *(const f32x4*)(W + (size_t)k * 12288); a1 += sm[k] * w; a2 += sm[DM + k] * w; }
	v_pk_fma_f32 v[2:3], v[70:71], v[110:111], v[2:3] op_sel_hi:[1,0,1]
	v_pk_fma_f32 v[0:1], v[68:69], v[110:111], v[0:1] op_sel_hi:[1,0,1]
	v_pk_fma_f32 v[6:7], v[70:71], v[110:111], v[6:7] op_sel:[0,1,0] op_sel_hi:[1,1,1]
	v_pk_fma_f32 v[4:5], v[68:69], v[110:111], v[4:5] op_sel:[0,1,0] op_sel_hi:[1,1,1]
	v_pk_fma_f32 v[2:3], v[74:75], v[112:113], v[2:3] op_sel_hi:[1,0,1]
	v_pk_fma_f32 v[0:1], v[72:73], v[112:113], v[0:1] op_sel_hi:[1,0,1]
	v_pk_fma_f32 v[6:7], v[74:75], v[112:113], v[6:7] op_sel:[0,1,0] op_sel_hi:[1,1,1]
	v_pk_fma_f32 v[4:5], v[72:73], v[112:113], v[4:5] op_sel:[0,1,0] op_sel_hi:[1,1,1]
	v_pk_fma_f32 v[2:3], v[78:79], v[114:115], v[2:3] op_sel_hi:[1,0,1]
	v_pk_fma_f32 v[0:1], v[76:77], v[114:115], v[0:1] op_sel_hi:[1,0,1]
	v_pk_fma_f32 v[6:7], v[78:79], v[114:115], v[6:7] op_sel:[0,1,0] op_sel_hi:[1,1,1]
	v_pk_fma_f32 v[4:5], v[76:77], v[114:115], v[4:5] op_sel:[0,1,0] op_sel_hi:[1,1,1]
	v_pk_fma_f32 v[2:3], v[82:83], v[116:117], v[2:3] op_sel_hi:[1,0,1]
	v_pk_fma_f32 v[0:1], v[80:81], v[116:117], v[0:1] op_sel_hi:[1,0,1]
	v_pk_fma_f32 v[6:7], v[82:83], v[116:117], v[6:7] op_sel:[0,1,0] op_sel_hi:[1,1,1]
	v_pk_fma_f32 v[4:5], v[80:81], v[116:117], v[4:5] op_sel:[0,1,0] op_sel_hi:[1,1,1]
	v_pk_fma_f32 v[2:3], v[86:87], v[118:119], v[2:3] op_sel_hi:[1,0,1]
	v_pk_fma_f32 v[0:1], v[84:85], v[118:119], v[0:1] op_sel_hi:[1,0,1]
	v_pk_fma_f32 v[6:7], v[86:87], v[118:119], v[6:7] op_sel:[0,1,0] op_sel_hi:[1,1,1]
	v_pk_fma_f32 v[4:5], v[84:85], v[118:119], v[4:5] op_sel:[0,1,0] op_sel_hi:[1,1,1]
	v_pk_fma_f32 v[2:3], v[90:91], v[120:121], v[2:3] op_sel_hi:[1,0,1]
	v_pk_fma_f32 v[0:1], v[88:89], v[120:121], v[0:1] op_sel_hi:[1,0,1]
	v_pk_fma_f32 v[6:7], v[90:91], v[120:121], v[6:7] op_sel:[0,1,0] op_sel_hi:[1,1,1]
	v_pk_fma_f32 v[4:5], v[88:89], v[120:121], v[4:5] op_sel:[0,1,0] op_sel_hi:[1,1,1]
	v_pk_fma_f32 v[2:3], v[94:95], v[122:123], v[2:3] op_sel_hi:[1,0,1]
	v_pk_fma_f32 v[0:1], v[92:93], v[122:123], v[0:1] op_sel_hi:[1,0,1]
	v_pk_fma_f32 v[6:7], v[94:95], v[122:123], v[6:7] op_sel:[0,1,0] op_sel_hi:[1,1,1]
	v_pk_fma_f32 v[4:5], v[92:93], v[122:123], v[4:5] op_sel:[0,1,0] op_sel_hi:[1,1,1]
	global_load_dwordx4 v[68:71], v[10:11], off
	ds_read2st64_b32 v[110:111], v12 offset1:32
	v_add_u32_e32 v12, 0x54, v12
	v_lshl_add_u64 v[10:11], v[10:11], 0, s[28:29]
	global_load_dwordx4 v[72:75], v[10:11], off
	ds_read2st64_b32 v[112:113], v12 offset1:32
	v_add_u32_e32 v12, 0x54, v12
	v_lshl_add_u64 v[10:11], v[10:11], 0, s[28:29]
	global_load_dwordx4 v[76:79], v[10:11], off
	ds_read2st64_b32 v[114:115], v12 offset1:32
	v_add_u32_e32 v12, 0x54, v12
	v_lshl_add_u64 v[10:11], v[10:11], 0, s[28:29]
	global_load_dwordx4 v[80:83], v[10:11], off
	ds_read2st64_b32 v[116:117], v12 offset1:32
	v_add_u32_e32 v12, 0x54, v12
	v_lshl_add_u64 v[10:11], v[10:11], 0, s[28:29]
	global_load_dwordx4 v[84:87], v[10:11], off
	ds_read2st64_b32 v[118:119], v12 offset1:32
	v_add_u32_e32 v12, 0x54, v12
	v_lshl_add_u64 v[10:11], v[10:11], 0, s[28:29]
	global_load_dwordx4 v[88:91], v[10:11], off
	ds_read2st64_b32 v[120:121], v12 offset1:32
	v_add_u32_e32 v12, 0x54, v12
	v_lshl_add_u64 v[10:11], v[10:11], 0, s[28:29]
	global_load_dwordx4 v[92:95], v[10:11], off
	ds_read2st64_b32 v[122:123], v12 offset1:32
	v_add_u32_e32 v12, 0x54, v12
	v_lshl_add_u64 v[10:11], v[10:11], 0, s[28:29]
	s_waitcnt vmcnt(7) lgkmcnt(7)
	v_pk_fma_f32 v[2:3], v[42:43], v[96:97], v[2:3] op_sel_hi:[1,0,1]
	v_pk_fma_f32 v[0:1], v[40:41], v[96:97], v[0:1] op_sel_hi:[1,0,1]
	v_pk_fma_f32 v[6:7], v[42:43], v[96:97], v[6:7] op_sel:[0,1,0] op_sel_hi:[1,1,1]
	v_pk_fma_f32 v[4:5], v[40:41], v[96:97], v[4:5] op_sel:[0,1,0] op_sel_hi:[1,1,1]
	v_pk_fma_f32 v[2:3], v[46:47], v[98:99], v[2:3] op_sel_hi:[1,0,1]
	v_pk_fma_f32 v[0:1], v[44:45], v[98:99], v[0:1] op_sel_hi:[1,0,1]
	v_pk_fma_f32 v[6:7], v[46:47], v[98:99], v[6:7] op_sel:[0,1,0] op_sel_hi:[1,1,1]
	v_pk_fma_f32 v[4:5], v[44:45], v[98:99], v[4:5] op_sel:[0,1,0] op_sel_hi:[1,1,1]
	v_pk_fma_f32 v[2:3], v[50:51], v[100:101], v[2:3] op_sel_hi:[1,0,1]
	v_pk_fma_f32 v[0:1], v[48:49], v[100:101], v[0:1] op_sel_hi:[1,0,1]
	v_pk_fma_f32 v[6:7], v[50:51], v[100:101], v[6:7] op_sel:[0,1,0] op_sel_hi:[1,1,1]
	v_pk_fma_f32 v[4:5], v[48:49], v[100:101], v[4:5] op_sel:[0,1,0] op_sel_hi:[1,1,1]
	v_pk_fma_f32 v[2:3], v[54:55], v[102:103], v[2:3] op_sel_hi:[1,0,1]
	v_pk_fma_f32 v[0:1], v[52:53], v[102:103], v[0:1] op_sel_hi:[1,0,1]
	v_pk_fma_f32 v[6:7], v[54:55], v[102:103], v[6:7] op_sel:[0,1,0] op_sel_hi:[1,1,1]
	v_pk_fma_f32 v[4:5], v[52:53], v[102:103], v[4:5] op_sel:[0,1,0] op_sel_hi:[1,1,1]
	v_pk_fma_f32 v[2:3], v[58:59], v[104:105], v[2:3] op_sel_hi:[1,0,1]
	v_pk_fma_f32 v[0:1], v[56:57], v[104:105], v[0:1] op_sel_hi:[1,0,1]
	v_pk_fma_f32 v[6:7], v[58:59], v[104:105], v[6:7] op_sel:[0,1,0] op_sel_hi:[1,1,1]
	v_pk_fma_f32 v[4:5], v[56:57], v[104:105], v[4:5] op_sel:[0,1,0] op_sel_hi:[1,1,1]
	v_pk_fma_f32 v[2:3], v[62:63], v[106:107], v[2:3] op_sel_hi:[1,0,1]
	v_pk_fma_f32 v[0:1], v[60:61], v[106:107], v[0:1] op_sel_hi:[1,0,1]
	v_pk_fma_f32 v[6:7], v[62:63], v[106:107], v[6:7] op_sel:[0,1,0] op_sel_hi:[1,1,1]
	v_pk_fma_f32 v[4:5], v[60:61], v[106:107], v[4:5] op_sel:[0,1,0] op_sel_hi:[1,1,1]
	v_pk_fma_f32 v[2:3], v[66:67], v[108:109], v[2:3] op_sel_hi:[1,0,1]
	v_pk_fma_f32 v[0:1], v[64:65], v[108:109], v[0:1] op_sel_hi:[1,0,1]
	v_pk_fma_f32 v[6:7], v[66:67], v[108:109], v[6:7] op_sel:[0,1,0] op_sel_hi:[1,1,1]
	v_pk_fma_f32 v[4:5], v[64:65], v[108:109], v[4:5] op_sel:[0,1,0] op_sel_hi:[1,1,1]
	global_load_dwordx4 v[40:43], v[10:11], off
	ds_read2st64_b32 v[96:97], v12 offset1:32
	v_add_u32_e32 v12, 0x54, v12
	v_lshl_add_u64 v[10:11], v[10:11], 0, s[28:29]
	global_load_dwordx4 v[44:47], v[10:11], off
	ds_read2st64_b32 v[98:99], v12 offset1:32
	v_add_u32_e32 v12, 0x54, v12
	v_lshl_add_u64 v[10:11], v[10:11], 0, s[28:29]
	global_load_dwordx4 v[48:51], v[10:11], off
	ds_read2st64_b32 v[100:101], v12 offset1:32
	v_add_u32_e32 v12, 0x54, v12
	v_lshl_add_u64 v[10:11], v[10:11], 0, s[28:29]
	global_load_dwordx4 v[52:55], v[10:11], off
	ds_read2st64_b32 v[102:103], v12 offset1:32
	v_add_u32_e32 v12, 0x54, v12
	v_lshl_add_u64 v[10:11], v[10:11], 0, s[28:29]
	global_load_dwordx4 v[56:59], v[10:11], off
	ds_read2st64_b32 v[104:105], v12 offset1:32
	v_add_u32_e32 v12, 0x54, v12
	v_lshl_add_u64 v[10:11], v[10:11], 0, s[28:29]
	global_load_dwordx4 v[60:63], v[10:11], off
	ds_read2st64_b32 v[106:107], v12 offset1:32
	v_add_u32_e32 v12, 0x54, v12
	v_lshl_add_u64 v[10:11], v[10:11], 0, s[28:29]
	global_load_dwordx4 v[64:67], v[10:11], off
	ds_read2st64_b32 v[108:109], v12 offset1:32
	v_add_u32_e32 v12, 0x54, v12
	v_lshl_add_u64 v[10:11], v[10:11], 0, s[28:29]
	s_waitcnt vmcnt(7) lgkmcnt(7)
; __device__ __forceinline__ void adaln_unit(KP p, int u, float* sm, int tid) {
;     ...
;     for (int k = rg; k < DM; k += 21) { const f32x4 w = *(const f32x4*)(W + (size_t)k * 12288); a1 += sm[k] * w; a2 += sm[DM + k] * w; }
	v_pk_fma_f32 v[2:3], v[70:71], v[110:111], v[2:3] op_sel_hi:[1,0,1]
	v_pk_fma_f32 v[0:1], v[68:69], v[110:111], v[0:1] op_sel_hi:[1,0,1]
	v_pk_fma_f32 v[6:7], v[70:71], v[110:111], v[6:7] op_sel:[0,1,0] op_sel_hi:[1,1,1]
	v_pk_fma_f32 v[4:5], v[68:69], v[110:111], v[4:5] op_sel:[0,1,0] op_sel_hi:[1,1,1]
	v_pk_fma_f32 v[2:3], v[74:75], v[112:113], v[2:3] op_sel_hi:[1,0,1]
	v_pk_fma_f32 v[0:1], v[72:73], v[112:113], v[0:1] op_sel_hi:[1,0,1]
	v_pk_fma_f32 v[6:7], v[74:75], v[112:113], v[6:7] op_sel:[0,1,0] op_sel_hi:[1,1,1]
	v_pk_fma_f32 v[4:5], v[72:73], v[112:113], v[4:5] op_sel:[0,1,0] op_sel_hi:[1,1,1]
	v_pk_fma_f32 v[2:3], v[78:79], v[114:115], v[2:3] op_sel_hi:[1,0,1]
	v_pk_fma_f32 v[0:1], v[76:77], v[114:115], v[0:1] op_sel_hi:[1,0,1]
	v_pk_fma_f32 v[6:7], v[78:79], v[114:115], v[6:7] op_sel:[0,1,0] op_sel_hi:[1,1,1]
	v_pk_fma_f32 v[4:5], v[76:77], v[114:115], v[4:5] op_sel:[0,1,0] op_sel_hi:[1,1,1]
	v_pk_fma_f32 v[2:3], v[82:83], v[116:117], v[2:3] op_sel_hi:[1,0,1]
	v_pk_fma_f32 v[0:1], v[80:81], v[116:117], v[0:1] op_sel_hi:[1,0,1]
	v_pk_fma_f32 v[6:7], v[82:83], v[116:117], v[6:7] op_sel:[0,1,0] op_sel_hi:[1,1,1]
	v_pk_fma_f32 v[4:5], v[80:81], v[116:117], v[4:5] op_sel:[0,1,0] op_sel_hi:[1,1,1]
	v_pk_fma_f32 v[2:3], v[86:87], v[118:119], v[2:3] op_sel_hi:[1,0,1]
	v_pk_fma_f32 v[0:1], v[84:85], v[118:119], v[0:1] op_sel_hi:[1,0,1]
	v_pk_fma_f32 v[6:7], v[86:87], v[118:119], v[6:7] op_sel:[0,1,0] op_sel_hi:[1,1,1]
	v_pk_fma_f32 v[4:5], v[84:85], v[118:119], v[4:5] op_sel:[0,1,0] op_sel_hi:[1,1,1]
	v_pk_fma_f32 v[2:3], v[90:91], v[120:121], v[2:3] op_sel_hi:[1,0,1]
	v_pk_fma_f32 v[0:1], v[88:89], v[120:121], v[0:1] op_sel_hi:[1,0,1]
	v_pk_fma_f32 v[6:7], v[90:91], v[120:121], v[6:7] op_sel:[0,1,0] op_sel_hi:[1,1,1]
	v_pk_fma_f32 v[4:5], v[88:89], v[120:121], v[4:5] op_sel:[0,1,0] op_sel_hi:[1,1,1]
	v_pk_fma_f32 v[2:3], v[94:95], v[122:123], v[2:3] op_sel_hi:[1,0,1]
	v_pk_fma_f32 v[0:1], v[92:93], v[122:123], v[0:1] op_sel_hi:[1,0,1]
	v_pk_fma_f32 v[6:7], v[94:95], v[122:123], v[6:7] op_sel:[0,1,0] op_sel_hi:[1,1,1]
	v_pk_fma_f32 v[4:5], v[92:93], v[122:123], v[4:5] op_sel:[0,1,0] op_sel_hi:[1,1,1]
	global_load_dwordx4 v[68:71], v[10:11], off
	ds_read2st64_b32 v[110:111], v12 offset1:32
	v_add_u32_e32 v12, 0x54, v12
	v_lshl_add_u64 v[10:11], v[10:11], 0, s[28:29]
	global_load_dwordx4 v[72:75], v[10:11], off
	ds_read2st64_b32 v[112:113], v12 offset1:32
	v_add_u32_e32 v12, 0x54, v12
	v_lshl_add_u64 v[10:11], v[10:11], 0, s[28:29]
	global_load_dwordx4 v[76:79], v[10:11], off
	ds_read2st64_b32 v[114:115], v12 offset1:32
	v_add_u32_e32 v12, 0x54, v12
	v_lshl_add_u64 v[10:11], v[10:11], 0, s[28:29]
	global_load_dwordx4 v[80:83], v[10:11], off
	ds_read2st64_b32 v[116:117], v12 offset1:32
	v_add_u32_e32 v12, 0x54, v12
	v_lshl_add_u64 v[10:11], v[10:11], 0, s[28:29]
	global_load_dwordx4 v[84:87], v[10:11], off
	ds_read2st64_b32 v[118:119], v12 offset1:32
	v_add_u32_e32 v12, 0x54, v12
	v_lshl_add_u64 v[10:11], v[10:11], 0, s[28:29]
	global_load_dwordx4 v[88:91], v[10:11], off
	ds_read2st64_b32 v[120:121], v12 offset1:32
	v_add_u32_e32 v12, 0x54, v12
	v_lshl_add_u64 v[10:11], v[10:11], 0, s[28:29]
	global_load_dwordx4 v[92:95], v[10:11], off
	ds_read2st64_b32 v[122:123], v12 offset1:32
	v_add_u32_e32 v12, 0x54, v12
	v_lshl_add_u64 v[10:11], v[10:11], 0, s[28:29]
	s_waitcnt vmcnt(7) lgkmcnt(7)
	v_pk_fma_f32 v[2:3], v[42:43], v[96:97], v[2:3] op_sel_hi:[1,0,1]
	v_pk_fma_f32 v[0:1], v[40:41], v[96:97], v[0:1] op_sel_hi:[1,0,1]
	v_pk_fma_f32 v[6:7], v[42:43], v[96:97], v[6:7] op_sel:[0,1,0] op_sel_hi:[1,1,1]
	v_pk_fma_f32 v[4:5], v[40:41], v[96:97], v[4:5] op_sel:[0,1,0] op_sel_hi:[1,1,1]
	v_pk_fma_f32 v[2:3], v[46:47], v[98:99], v[2:3] op_sel_hi:[1,0,1]
	v_pk_fma_f32 v[0:1], v[44:45], v[98:99], v[0:1] op_sel_hi:[1,0,1]
	v_pk_fma_f32 v[6:7], v[46:47], v[98:99], v[6:7] op_sel:[0,1,0] op_sel_hi:[1,1,1]
	v_pk_fma_f32 v[4:5], v[44:45], v[98:99], v[4:5] op_sel:[0,1,0] op_sel_hi:[1,1,1]
	v_pk_fma_f32 v[2:3], v[50:51], v[100:101], v[2:3] op_sel_hi:[1,0,1]
	v_pk_fma_f32 v[0:1], v[48:49], v[100:101], v[0:1] op_sel_hi:[1,0,1]
	v_pk_fma_f32 v[6:7], v[50:51], v[100:101], v[6:7] op_sel:[0,1,0] op_sel_hi:[1,1,1]
	v_pk_fma_f32 v[4:5], v[48:49], v[100:101], v[4:5] op_sel:[0,1,0] op_sel_hi:[1,1,1]
	v_pk_fma_f32 v[2:3], v[54:55], v[102:103], v[2:3] op_sel_hi:[1,0,1]
	v_pk_fma_f32 v[0:1], v[52:53], v[102:103], v[0:1] op_sel_hi:[1,0,1]
	v_pk_fma_f32 v[6:7], v[54:55], v[102:103], v[6:7] op_sel:[0,1,0] op_sel_hi:[1,1,1]
	v_pk_fma_f32 v[4:5], v[52:53], v[102:103], v[4:5] op_sel:[0,1,0] op_sel_hi:[1,1,1]
	v_pk_fma_f32 v[2:3], v[58:59], v[104:105], v[2:3] op_sel_hi:[1,0,1]
	v_pk_fma_f32 v[0:1], v[56:57], v[104:105], v[0:1] op_sel_hi:[1,0,1]
	v_pk_fma_f32 v[6:7], v[58:59], v[104:105], v[6:7] op_sel:[0,1,0] op_sel_hi:[1,1,1]
	v_pk_fma_f32 v[4:5], v[56:57], v[104:105], v[4:5] op_sel:[0,1,0] op_sel_hi:[1,1,1]
	v_pk_fma_f32 v[2:3], v[62:63], v[106:107], v[2:3] op_sel_hi:[1,0,1]
	v_pk_fma_f32 v[0:1], v[60:61], v[106:107], v[0:1] op_sel_hi:[1,0,1]
	v_pk_fma_f32 v[6:7], v[62:63], v[106:107], v[6:7] op_sel:[0,1,0] op_sel_hi:[1,1,1]
	v_pk_fma_f32 v[4:5], v[60:61], v[106:107], v[4:5] op_sel:[0,1,0] op_sel_hi:[1,1,1]
	v_pk_fma_f32 v[2:3], v[66:67], v[108:109], v[2:3] op_sel_hi:[1,0,1]
	v_pk_fma_f32 v[0:1], v[64:65], v[108:109], v[0:1] op_sel_hi:[1,0,1]
	v_pk_fma_f32 v[6:7], v[66:67], v[108:109], v[6:7] op_sel:[0,1,0] op_sel_hi:[1,1,1]
	v_pk_fma_f32 v[4:5], v[64:65], v[108:109], v[4:5] op_sel:[0,1,0] op_sel_hi:[1,1,1]
	global_load_dwordx4 v[40:43], v[10:11], off
	ds_read2st64_b32 v[96:97], v12 offset1:32
	v_add_u32_e32 v12, 0x54, v12
	v_lshl_add_u64 v[10:11], v[10:11], 0, s[28:29]
	global_load_dwordx4 v[44:47], v[10:11], off
	ds_read2st64_b32 v[98:99], v12 offset1:32
	v_add_u32_e32 v12, 0x54, v12
	v_lshl_add_u64 v[10:11], v[10:11], 0, s[28:29]
	global_load_dwordx4 v[48:51], v[10:11], off
	ds_read2st64_b32 v[100:101], v12 offset1:32
	v_add_u32_e32 v12, 0x54, v12
	v_lshl_add_u64 v[10:11], v[10:11], 0, s[28:29]
	global_load_dwordx4 v[52:55], v[10:11], off
	ds_read2st64_b32 v[102:103], v12 offset1:32
	v_add_u32_e32 v12, 0x54, v12
	v_lshl_add_u64 v[10:11], v[10:11], 0, s[28:29]
	global_load_dwordx4 v[56:59], v[10:11], off
	ds_read2st64_b32 v[104:105], v12 offset1:32
	v_add_u32_e32 v12, 0x54, v12
	v_lshl_add_u64 v[10:11], v[10:11], 0, s[28:29]
	global_load_dwordx4 v[60:63], v[10:11], off
	ds_read2st64_b32 v[106:107], v12 offset1:32
	v_add_u32_e32 v12, 0x54, v12
	v_lshl_add_u64 v[10:11], v[10:11], 0, s[28:29]
	global_load_dwordx4 v[64:67], v[10:11], off
	ds_read2st64_b32 v[108:109], v12 offset1:32
	v_add_u32_e32 v12, 0x54, v12
	v_lshl_add_u64 v[10:11], v[10:11], 0, s[28:29]
	s_waitcnt vmcnt(7) lgkmcnt(7)
; __device__ __forceinline__ void adaln_unit(KP p, int u, float* sm, int tid) {
;     ...
;     const float* W = p->in[6] + (size_t)l * DM * 12288 + j0 + 4 * c4;
;     for (int k = rg; k < DM; k += 21) { const f32x4 w = *(const f32x4*)(W + (size_t)k * 12288); a1 += sm[k] * w; a2 += sm[DM + k] * w; }
	v_pk_fma_f32 v[2:3], v[70:71], v[110:111], v[2:3] op_sel_hi:[1,0,1]
	v_pk_fma_f32 v[0:1], v[68:69], v[110:111], v[0:1] op_sel_hi:[1,0,1]
	v_pk_fma_f32 v[6:7], v[70:71], v[110:111], v[6:7] op_sel:[0,1,0] op_sel_hi:[1,1,1]
	v_pk_fma_f32 v[4:5], v[68:69], v[110:111], v[4:5] op_sel:[0,1,0] op_sel_hi:[1,1,1]
	v_pk_fma_f32 v[2:3], v[74:75], v[112:113], v[2:3] op_sel_hi:[1,0,1]
	v_pk_fma_f32 v[0:1], v[72:73], v[112:113], v[0:1] op_sel_hi:[1,0,1]
	v_pk_fma_f32 v[6:7], v[74:75], v[112:113], v[6:7] op_sel:[0,1,0] op_sel_hi:[1,1,1]
	v_pk_fma_f32 v[4:5], v[72:73], v[112:113], v[4:5] op_sel:[0,1,0] op_sel_hi:[1,1,1]
	v_pk_fma_f32 v[2:3], v[78:79], v[114:115], v[2:3] op_sel_hi:[1,0,1]
	v_pk_fma_f32 v[0:1], v[76:77], v[114:115], v[0:1] op_sel_hi:[1,0,1]
	v_pk_fma_f32 v[6:7], v[78:79], v[114:115], v[6:7] op_sel:[0,1,0] op_sel_hi:[1,1,1]
	v_pk_fma_f32 v[4:5], v[76:77], v[114:115], v[4:5] op_sel:[0,1,0] op_sel_hi:[1,1,1]
	v_pk_fma_f32 v[2:3], v[82:83], v[116:117], v[2:3] op_sel_hi:[1,0,1]
	v_pk_fma_f32 v[0:1], v[80:81], v[116:117], v[0:1] op_sel_hi:[1,0,1]
	v_pk_fma_f32 v[6:7], v[82:83], v[116:117], v[6:7] op_sel:[0,1,0] op_sel_hi:[1,1,1]
	v_pk_fma_f32 v[4:5], v[80:81], v[116:117], v[4:5] op_sel:[0,1,0] op_sel_hi:[1,1,1]
	v_pk_fma_f32 v[2:3], v[86:87], v[118:119], v[2:3] op_sel_hi:[1,0,1]
	v_pk_fma_f32 v[0:1], v[84:85], v[118:119], v[0:1] op_sel_hi:[1,0,1]
	v_pk_fma_f32 v[6:7], v[86:87], v[118:119], v[6:7] op_sel:[0,1,0] op_sel_hi:[1,1,1]
	v_pk_fma_f32 v[4:5], v[84:85], v[118:119], v[4:5] op_sel:[0,1,0] op_sel_hi:[1,1,1]
	v_pk_fma_f32 v[2:3], v[90:91], v[120:121], v[2:3] op_sel_hi:[1,0,1]
	v_pk_fma_f32 v[0:1], v[88:89], v[120:121], v[0:1] op_sel_hi:[1,0,1]
	v_pk_fma_f32 v[6:7], v[90:91], v[120:121], v[6:7] op_sel:[0,1,0] op_sel_hi:[1,1,1]
	v_pk_fma_f32 v[4:5], v[88:89], v[120:121], v[4:5] op_sel:[0,1,0] op_sel_hi:[1,1,1]
	v_pk_fma_f32 v[2:3], v[94:95], v[122:123], v[2:3] op_sel_hi:[1,0,1]
	v_pk_fma_f32 v[0:1], v[92:93], v[122:123], v[0:1] op_sel_hi:[1,0,1]
	v_pk_fma_f32 v[6:7], v[94:95], v[122:123], v[6:7] op_sel:[0,1,0] op_sel_hi:[1,1,1]
	v_pk_fma_f32 v[4:5], v[92:93], v[122:123], v[4:5] op_sel:[0,1,0] op_sel_hi:[1,1,1]
	global_load_dwordx4 v[68:71], v[10:11], off
	ds_read2st64_b32 v[110:111], v12 offset1:32
	v_add_u32_e32 v12, 0x54, v12
	v_lshl_add_u64 v[10:11], v[10:11], 0, s[28:29]
	global_load_dwordx4 v[72:75], v[10:11], off
	ds_read2st64_b32 v[112:113], v12 offset1:32
	v_add_u32_e32 v12, 0x54, v12
	v_lshl_add_u64 v[10:11], v[10:11], 0, s[28:29]
	global_load_dwordx4 v[76:79], v[10:11], off
	ds_read2st64_b32 v[114:115], v12 offset1:32
	v_add_u32_e32 v12, 0x54, v12
	v_lshl_add_u64 v[10:11], v[10:11], 0, s[28:29]
	global_load_dwordx4 v[80:83], v[10:11], off
	ds_read2st64_b32 v[116:117], v12 offset1:32
	v_add_u32_e32 v12, 0x54, v12
	v_lshl_add_u64 v[10:11], v[10:11], 0, s[28:29]
	global_load_dwordx4 v[84:87], v[10:11], off
	ds_read2st64_b32 v[118:119], v12 offset1:32
	v_add_u32_e32 v12, 0x54, v12
	v_lshl_add_u64 v[10:11], v[10:11], 0, s[28:29]
	global_load_dwordx4 v[88:91], v[10:11], off
	ds_read2st64_b32 v[120:121], v12 offset1:32
	v_add_u32_e32 v12, 0x54, v12
	v_lshl_add_u64 v[10:11], v[10:11], 0, s[28:29]
	global_load_dwordx4 v[92:95], v[10:11], off
	ds_read2st64_b32 v[122:123], v12 offset1:32
	v_add_u32_e32 v12, 0x54, v12
	v_lshl_add_u64 v[10:11], v[10:11], 0, s[28:29]
	s_waitcnt vmcnt(7) lgkmcnt(7)
	v_pk_fma_f32 v[2:3], v[42:43], v[96:97], v[2:3] op_sel_hi:[1,0,1]
	v_pk_fma_f32 v[0:1], v[40:41], v[96:97], v[0:1] op_sel_hi:[1,0,1]
	v_pk_fma_f32 v[6:7], v[42:43], v[96:97], v[6:7] op_sel:[0,1,0] op_sel_hi:[1,1,1]
	v_pk_fma_f32 v[4:5], v[40:41], v[96:97], v[4:5] op_sel:[0,1,0] op_sel_hi:[1,1,1]
	v_pk_fma_f32 v[2:3], v[46:47], v[98:99], v[2:3] op_sel_hi:[1,0,1]
	v_pk_fma_f32 v[0:1], v[44:45], v[98:99], v[0:1] op_sel_hi:[1,0,1]
	v_pk_fma_f32 v[6:7], v[46:47], v[98:99], v[6:7] op_sel:[0,1,0] op_sel_hi:[1,1,1]
	v_pk_fma_f32 v[4:5], v[44:45], v[98:99], v[4:5] op_sel:[0,1,0] op_sel_hi:[1,1,1]
	v_pk_fma_f32 v[2:3], v[50:51], v[100:101], v[2:3] op_sel_hi:[1,0,1]
	v_pk_fma_f32 v[0:1], v[48:49], v[100:101], v[0:1] op_sel_hi:[1,0,1]
	v_pk_fma_f32 v[6:7], v[50:51], v[100:101], v[6:7] op_sel:[0,1,0] op_sel_hi:[1,1,1]
	v_pk_fma_f32 v[4:5], v[48:49], v[100:101], v[4:5] op_sel:[0,1,0] op_sel_hi:[1,1,1]
	v_pk_fma_f32 v[2:3], v[54:55], v[102:103], v[2:3] op_sel_hi:[1,0,1]
	v_pk_fma_f32 v[0:1], v[52:53], v[102:103], v[0:1] op_sel_hi:[1,0,1]
	v_pk_fma_f32 v[6:7], v[54:55], v[102:103], v[6:7] op_sel:[0,1,0] op_sel_hi:[1,1,1]
	v_pk_fma_f32 v[4:5], v[52:53], v[102:103], v[4:5] op_sel:[0,1,0] op_sel_hi:[1,1,1]
	v_pk_fma_f32 v[2:3], v[58:59], v[104:105], v[2:3] op_sel_hi:[1,0,1]
	v_pk_fma_f32 v[0:1], v[56:57], v[104:105], v[0:1] op_sel_hi:[1,0,1]
	v_pk_fma_f32 v[6:7], v[58:59], v[104:105], v[6:7] op_sel:[0,1,0] op_sel_hi:[1,1,1]
	v_pk_fma_f32 v[4:5], v[56:57], v[104:105], v[4:5] op_sel:[0,1,0] op_sel_hi:[1,1,1]
	v_pk_fma_f32 v[2:3], v[62:63], v[106:107], v[2:3] op_sel_hi:[1,0,1]
	v_pk_fma_f32 v[0:1], v[60:61], v[106:107], v[0:1] op_sel_hi:[1,0,1]
	v_pk_fma_f32 v[6:7], v[62:63], v[106:107], v[6:7] op_sel:[0,1,0] op_sel_hi:[1,1,1]
	v_pk_fma_f32 v[4:5], v[60:61], v[106:107], v[4:5] op_sel:[0,1,0] op_sel_hi:[1,1,1]
	v_pk_fma_f32 v[2:3], v[66:67], v[108:109], v[2:3] op_sel_hi:[1,0,1]
	v_pk_fma_f32 v[0:1], v[64:65], v[108:109], v[0:1] op_sel_hi:[1,0,1]
	v_pk_fma_f32 v[6:7], v[66:67], v[108:109], v[6:7] op_sel:[0,1,0] op_sel_hi:[1,1,1]
	v_pk_fma_f32 v[4:5], v[64:65], v[108:109], v[4:5] op_sel:[0,1,0] op_sel_hi:[1,1,1]
	global_load_dwordx4 v[40:43], v[10:11], off
	ds_read2st64_b32 v[96:97], v12 offset1:32
	v_add_u32_e32 v12, 0x54, v12
	v_lshl_add_u64 v[10:11], v[10:11], 0, s[28:29]
	global_load_dwordx4 v[44:47], v[10:11], off
	ds_read2st64_b32 v[98:99], v12 offset1:32
	v_add_u32_e32 v12, 0x54, v12
	v_lshl_add_u64 v[10:11], v[10:11], 0, s[28:29]
	global_load_dwordx4 v[48:51], v[10:11], off
	ds_read2st64_b32 v[100:101], v12 offset1:32
	v_add_u32_e32 v12, 0x54, v12
	v_lshl_add_u64 v[10:11], v[10:11], 0, s[28:29]
	global_load_dwordx4 v[52:55], v[10:11], off
	ds_read2st64_b32 v[102:103], v12 offset1:32
	v_add_u32_e32 v12, 0x54, v12
	v_lshl_add_u64 v[10:11], v[10:11], 0, s[28:29]
	global_load_dwordx4 v[56:59], v[10:11], off
	ds_read2st64_b32 v[104:105], v12 offset1:32
	v_add_u32_e32 v12, 0x54, v12
	v_lshl_add_u64 v[10:11], v[10:11], 0, s[28:29]
	global_load_dwordx4 v[60:63], v[10:11], off
	ds_read2st64_b32 v[106:107], v12 offset1:32
	v_add_u32_e32 v12, 0x54, v12
	v_lshl_add_u64 v[10:11], v[10:11], 0, s[28:29]
	global_load_dwordx4 v[64:67], v[10:11], off
	ds_read2st64_b32 v[108:109], v12 offset1:32
	v_add_u32_e32 v12, 0x54, v12
	v_lshl_add_u64 v[10:11], v[10:11], 0, s[28:29]
	s_waitcnt vmcnt(7) lgkmcnt(7)
; __device__ __forceinline__ void adaln_unit(KP p, int u, float* sm, int tid) {
;     ...
;     const float* W = p->in[6] + (size_t)l * DM * 12288 + j0 + 4 * c4;
;     for (int k = rg; k < DM; k += 21) { const f32x4 w = *(const f32x4*)(W + (size_t)k * 12288); a1 += sm[k] * w; a2 += sm[DM + k] * w; }
	v_pk_fma_f32 v[2:3], v[70:71], v[110:111], v[2:3] op_sel_hi:[1,0,1]
	v_pk_fma_f32 v[0:1], v[68:69], v[110:111], v[0:1] op_sel_hi:[1,0,1]
	v_pk_fma_f32 v[6:7], v[70:71], v[110:111], v[6:7] op_sel:[0,1,0] op_sel_hi:[1,1,1]
	v_pk_fma_f32 v[4:5], v[68:69], v[110:111], v[4:5] op_sel:[0,1,0] op_sel_hi:[1,1,1]
	v_pk_fma_f32 v[2:3], v[74:75], v[112:113], v[2:3] op_sel_hi:[1,0,1]
	v_pk_fma_f32 v[0:1], v[72:73], v[112:113], v[0:1] op_sel_hi:[1,0,1]
	v_pk_fma_f32 v[6:7], v[74:75], v[112:113], v[6:7] op_sel:[0,1,0] op_sel_hi:[1,1,1]
	v_pk_fma_f32 v[4:5], v[72:73], v[112:113], v[4:5] op_sel:[0,1,0] op_sel_hi:[1,1,1]
	v_pk_fma_f32 v[2:3], v[78:79], v[114:115], v[2:3] op_sel_hi:[1,0,1]
	v_pk_fma_f32 v[0:1], v[76:77], v[114:115], v[0:1] op_sel_hi:[1,0,1]
	v_pk_fma_f32 v[6:7], v[78:79], v[114:115], v[6:7] op_sel:[0,1,0] op_sel_hi:[1,1,1]
	v_pk_fma_f32 v[4:5], v[76:77], v[114:115], v[4:5] op_sel:[0,1,0] op_sel_hi:[1,1,1]
	v_pk_fma_f32 v[2:3], v[82:83], v[116:117], v[2:3] op_sel_hi:[1,0,1]
	v_pk_fma_f32 v[0:1], v[80:81], v[116:117], v[0:1] op_sel_hi:[1,0,1]
	v_pk_fma_f32 v[6:7], v[82:83], v[116:117], v[6:7] op_sel:[0,1,0] op_sel_hi:[1,1,1]
	v_pk_fma_f32 v[4:5], v[80:81], v[116:117], v[4:5] op_sel:[0,1,0] op_sel_hi:[1,1,1]
	v_pk_fma_f32 v[2:3], v[86:87], v[118:119], v[2:3] op_sel_hi:[1,0,1]
	v_pk_fma_f32 v[0:1], v[84:85], v[118:119], v[0:1] op_sel_hi:[1,0,1]
	v_pk_fma_f32 v[6:7], v[86:87], v[118:119], v[6:7] op_sel:[0,1,0] op_sel_hi:[1,1,1]
	v_pk_fma_f32 v[4:5], v[84:85], v[118:119], v[4:5] op_sel:[0,1,0] op_sel_hi:[1,1,1]
	v_pk_fma_f32 v[2:3], v[90:91], v[120:121], v[2:3] op_sel_hi:[1,0,1]
	v_pk_fma_f32 v[0:1], v[88:89], v[120:121], v[0:1] op_sel_hi:[1,0,1]
	v_pk_fma_f32 v[6:7], v[90:91], v[120:121], v[6:7] op_sel:[0,1,0] op_sel_hi:[1,1,1]
	v_pk_fma_f32 v[4:5], v[88:89], v[120:121], v[4:5] op_sel:[0,1,0] op_sel_hi:[1,1,1]
	v_pk_fma_f32 v[2:3], v[94:95], v[122:123], v[2:3] op_sel_hi:[1,0,1]
	v_pk_fma_f32 v[0:1], v[92:93], v[122:123], v[0:1] op_sel_hi:[1,0,1]
	v_pk_fma_f32 v[6:7], v[94:95], v[122:123], v[6:7] op_sel:[0,1,0] op_sel_hi:[1,1,1]
	v_pk_fma_f32 v[4:5], v[92:93], v[122:123], v[4:5] op_sel:[0,1,0] op_sel_hi:[1,1,1]
	global_load_dwordx4 v[68:71], v[10:11], off
	ds_read2st64_b32 v[110:111], v12 offset1:32
	v_add_u32_e32 v12, 0x54, v12
	v_lshl_add_u64 v[10:11], v[10:11], 0, s[28:29]
	global_load_dwordx4 v[72:75], v[10:11], off
	ds_read2st64_b32 v[112:113], v12 offset1:32
	v_add_u32_e32 v12, 0x54, v12
	v_lshl_add_u64 v[10:11], v[10:11], 0, s[28:29]
	global_load_dwordx4 v[76:79], v[10:11], off
	ds_read2st64_b32 v[114:115], v12 offset1:32
	v_add_u32_e32 v12, 0x54, v12
	v_lshl_add_u64 v[10:11], v[10:11], 0, s[28:29]
	global_load_dwordx4 v[80:83], v[10:11], off
	ds_read2st64_b32 v[116:117], v12 offset1:32
	v_add_u32_e32 v12, 0x54, v12
	v_lshl_add_u64 v[10:11], v[10:11], 0, s[28:29]
	global_load_dwordx4 v[84:87], v[10:11], off
	ds_read2st64_b32 v[118:119], v12 offset1:32
	v_add_u32_e32 v12, 0x54, v12
	v_lshl_add_u64 v[10:11], v[10:11], 0, s[28:29]
	global_load_dwordx4 v[88:91], v[10:11], off
	ds_read2st64_b32 v[120:121], v12 offset1:32
	v_add_u32_e32 v12, 0x54, v12
	v_lshl_add_u64 v[10:11], v[10:11], 0, s[28:29]
	global_load_dwordx4 v[92:95], v[10:11], off
	ds_read2st64_b32 v[122:123], v12 offset1:32
	v_add_u32_e32 v12, 0x54, v12
	v_lshl_add_u64 v[10:11], v[10:11], 0, s[28:29]
	s_waitcnt vmcnt(7) lgkmcnt(7)
	v_pk_fma_f32 v[2:3], v[42:43], v[96:97], v[2:3] op_sel_hi:[1,0,1]
	v_pk_fma_f32 v[0:1], v[40:41], v[96:97], v[0:1] op_sel_hi:[1,0,1]
	v_pk_fma_f32 v[6:7], v[42:43], v[96:97], v[6:7] op_sel:[0,1,0] op_sel_hi:[1,1,1]
	v_pk_fma_f32 v[4:5], v[40:41], v[96:97], v[4:5] op_sel:[0,1,0] op_sel_hi:[1,1,1]
	v_pk_fma_f32 v[2:3], v[46:47], v[98:99], v[2:3] op_sel_hi:[1,0,1]
	v_pk_fma_f32 v[0:1], v[44:45], v[98:99], v[0:1] op_sel_hi:[1,0,1]
	v_pk_fma_f32 v[6:7], v[46:47], v[98:99], v[6:7] op_sel:[0,1,0] op_sel_hi:[1,1,1]
	v_pk_fma_f32 v[4:5], v[44:45], v[98:99], v[4:5] op_sel:[0,1,0] op_sel_hi:[1,1,1]
	v_pk_fma_f32 v[2:3], v[50:51], v[100:101], v[2:3] op_sel_hi:[1,0,1]
	v_pk_fma_f32 v[0:1], v[48:49], v[100:101], v[0:1] op_sel_hi:[1,0,1]
	v_pk_fma_f32 v[6:7], v[50:51], v[100:101], v[6:7] op_sel:[0,1,0] op_sel_hi:[1,1,1]
	v_pk_fma_f32 v[4:5], v[48:49], v[100:101], v[4:5] op_sel:[0,1,0] op_sel_hi:[1,1,1]
	v_pk_fma_f32 v[2:3], v[54:55], v[102:103], v[2:3] op_sel_hi:[1,0,1]
	v_pk_fma_f32 v[0:1], v[52:53], v[102:103], v[0:1] op_sel_hi:[1,0,1]
	v_pk_fma_f32 v[6:7], v[54:55], v[102:103], v[6:7] op_sel:[0,1,0] op_sel_hi:[1,1,1]
	v_pk_fma_f32 v[4:5], v[52:53], v[102:103], v[4:5] op_sel:[0,1,0] op_sel_hi:[1,1,1]
	v_pk_fma_f32 v[2:3], v[58:59], v[104:105], v[2:3] op_sel_hi:[1,0,1]
	v_pk_fma_f32 v[0:1], v[56:57], v[104:105], v[0:1] op_sel_hi:[1,0,1]
	v_pk_fma_f32 v[6:7], v[58:59], v[104:105], v[6:7] op_sel:[0,1,0] op_sel_hi:[1,1,1]
	v_pk_fma_f32 v[4:5], v[56:57], v[104:105], v[4:5] op_sel:[0,1,0] op_sel_hi:[1,1,1]
	v_pk_fma_f32 v[2:3], v[62:63], v[106:107], v[2:3] op_sel_hi:[1,0,1]
	v_pk_fma_f32 v[0:1], v[60:61], v[106:107], v[0:1] op_sel_hi:[1,0,1]
	v_pk_fma_f32 v[6:7], v[62:63], v[106:107], v[6:7] op_sel:[0,1,0] op_sel_hi:[1,1,1]
	v_pk_fma_f32 v[4:5], v[60:61], v[106:107], v[4:5] op_sel:[0,1,0] op_sel_hi:[1,1,1]
	v_pk_fma_f32 v[2:3], v[66:67], v[108:109], v[2:3] op_sel_hi:[1,0,1]
	v_pk_fma_f32 v[0:1], v[64:65], v[108:109], v[0:1] op_sel_hi:[1,0,1]
	v_pk_fma_f32 v[6:7], v[66:67], v[108:109], v[6:7] op_sel:[0,1,0] op_sel_hi:[1,1,1]
	v_pk_fma_f32 v[4:5], v[64:65], v[108:109], v[4:5] op_sel:[0,1,0] op_sel_hi:[1,1,1]
	global_load_dwordx4 v[40:43], v[10:11], off
	ds_read2st64_b32 v[96:97], v12 offset1:32
	v_add_u32_e32 v12, 0x54, v12
	v_lshl_add_u64 v[10:11], v[10:11], 0, s[28:29]
	global_load_dwordx4 v[44:47], v[10:11], off
	ds_read2st64_b32 v[98:99], v12 offset1:32
	v_add_u32_e32 v12, 0x54, v12
	v_lshl_add_u64 v[10:11], v[10:11], 0, s[28:29]
	global_load_dwordx4 v[48:51], v[10:11], off
	ds_read2st64_b32 v[100:101], v12 offset1:32
	v_add_u32_e32 v12, 0x54, v12
	v_lshl_add_u64 v[10:11], v[10:11], 0, s[28:29]
	global_load_dwordx4 v[52:55], v[10:11], off
	ds_read2st64_b32 v[102:103], v12 offset1:32
	v_add_u32_e32 v12, 0x54, v12
	v_lshl_add_u64 v[10:11], v[10:11], 0, s[28:29]
	global_load_dwordx4 v[56:59], v[10:11], off
	ds_read2st64_b32 v[104:105], v12 offset1:32
	v_add_u32_e32 v12, 0x54, v12
	v_lshl_add_u64 v[10:11], v[10:11], 0, s[28:29]
	global_load_dwordx4 v[60:63], v[10:11], off
	ds_read2st64_b32 v[106:107], v12 offset1:32
	v_add_u32_e32 v12, 0x54, v12
	v_lshl_add_u64 v[10:11], v[10:11], 0, s[28:29]
	global_load_dwordx4 v[64:67], v[10:11], off
	ds_read2st64_b32 v[108:109], v12 offset1:32
	v_add_u32_e32 v12, 0x54, v12
	v_lshl_add_u64 v[10:11], v[10:11], 0, s[28:29]
	s_waitcnt vmcnt(7) lgkmcnt(7)
; __device__ __forceinline__ void adaln_unit(KP p, int u, float* sm, int tid) {
;     ...
;     const float* W = p->in[6] + (size_t)l * DM * 12288 + j0 + 4 * c4;
;     for (int k = rg; k < DM; k += 21) { const f32x4 w = *(const f32x4*)(W + (size_t)k * 12288); a1 += sm[k] * w; a2 += sm[DM + k] * w; }
	v_pk_fma_f32 v[2:3], v[70:71], v[110:111], v[2:3] op_sel_hi:[1,0,1]
	v_pk_fma_f32 v[0:1], v[68:69], v[110:111], v[0:1] op_sel_hi:[1,0,1]
	v_pk_fma_f32 v[6:7], v[70:71], v[110:111], v[6:7] op_sel:[0,1,0] op_sel_hi:[1,1,1]
	v_pk_fma_f32 v[4:5], v[68:69], v[110:111], v[4:5] op_sel:[0,1,0] op_sel_hi:[1,1,1]
	v_pk_fma_f32 v[2:3], v[74:75], v[112:113], v[2:3] op_sel_hi:[1,0,1]
	v_pk_fma_f32 v[0:1], v[72:73], v[112:113], v[0:1] op_sel_hi:[1,0,1]
	v_pk_fma_f32 v[6:7], v[74:75], v[112:113], v[6:7] op_sel:[0,1,0] op_sel_hi:[1,1,1]
	v_pk_fma_f32 v[4:5], v[72:73], v[112:113], v[4:5] op_sel:[0,1,0] op_sel_hi:[1,1,1]
	v_pk_fma_f32 v[2:3], v[78:79], v[114:115], v[2:3] op_sel_hi:[1,0,1]
	v_pk_fma_f32 v[0:1], v[76:77], v[114:115], v[0:1] op_sel_hi:[1,0,1]
	v_pk_fma_f32 v[6:7], v[78:79], v[114:115], v[6:7] op_sel:[0,1,0] op_sel_hi:[1,1,1]
	v_pk_fma_f32 v[4:5], v[76:77], v[114:115], v[4:5] op_sel:[0,1,0] op_sel_hi:[1,1,1]
	v_pk_fma_f32 v[2:3], v[82:83], v[116:117], v[2:3] op_sel_hi:[1,0,1]
	v_pk_fma_f32 v[0:1], v[80:81], v[116:117], v[0:1] op_sel_hi:[1,0,1]
	v_pk_fma_f32 v[6:7], v[82:83], v[116:117], v[6:7] op_sel:[0,1,0] op_sel_hi:[1,1,1]
	v_pk_fma_f32 v[4:5], v[80:81], v[116:117], v[4:5] op_sel:[0,1,0] op_sel_hi:[1,1,1]
	v_pk_fma_f32 v[2:3], v[86:87], v[118:119], v[2:3] op_sel_hi:[1,0,1]
	v_pk_fma_f32 v[0:1], v[84:85], v[118:119], v[0:1] op_sel_hi:[1,0,1]
	v_pk_fma_f32 v[6:7], v[86:87], v[118:119], v[6:7] op_sel:[0,1,0] op_sel_hi:[1,1,1]
	v_pk_fma_f32 v[4:5], v[84:85], v[118:119], v[4:5] op_sel:[0,1,0] op_sel_hi:[1,1,1]
	v_pk_fma_f32 v[2:3], v[90:91], v[120:121], v[2:3] op_sel_hi:[1,0,1]
	v_pk_fma_f32 v[0:1], v[88:89], v[120:121], v[0:1] op_sel_hi:[1,0,1]
	v_pk_fma_f32 v[6:7], v[90:91], v[120:121], v[6:7] op_sel:[0,1,0] op_sel_hi:[1,1,1]
	v_pk_fma_f32 v[4:5], v[88:89], v[120:121], v[4:5] op_sel:[0,1,0] op_sel_hi:[1,1,1]
	v_pk_fma_f32 v[2:3], v[94:95], v[122:123], v[2:3] op_sel_hi:[1,0,1]
	v_pk_fma_f32 v[0:1], v[92:93], v[122:123], v[0:1] op_sel_hi:[1,0,1]
	v_pk_fma_f32 v[6:7], v[94:95], v[122:123], v[6:7] op_sel:[0,1,0] op_sel_hi:[1,1,1]
	v_pk_fma_f32 v[4:5], v[92:93], v[122:123], v[4:5] op_sel:[0,1,0] op_sel_hi:[1,1,1]
	global_load_dwordx4 v[68:71], v[10:11], off
	ds_read2st64_b32 v[110:111], v12 offset1:32
	v_add_u32_e32 v12, 0x54, v12
	v_lshl_add_u64 v[10:11], v[10:11], 0, s[28:29]
	global_load_dwordx4 v[72:75], v[10:11], off
	ds_read2st64_b32 v[112:113], v12 offset1:32
	v_add_u32_e32 v12, 0x54, v12
	v_lshl_add_u64 v[10:11], v[10:11], 0, s[28:29]
	global_load_dwordx4 v[76:79], v[10:11], off
	ds_read2st64_b32 v[114:115], v12 offset1:32
	v_add_u32_e32 v12, 0x54, v12
	v_lshl_add_u64 v[10:11], v[10:11], 0, s[28:29]
	global_load_dwordx4 v[80:83], v[10:11], off
	ds_read2st64_b32 v[116:117], v12 offset1:32
	v_add_u32_e32 v12, 0x54, v12
	v_lshl_add_u64 v[10:11], v[10:11], 0, s[28:29]
	global_load_dwordx4 v[84:87], v[10:11], off
	ds_read2st64_b32 v[118:119], v12 offset1:32
	v_add_u32_e32 v12, 0x54, v12
	v_lshl_add_u64 v[10:11], v[10:11], 0, s[28:29]
	global_load_dwordx4 v[88:91], v[10:11], off
	ds_read2st64_b32 v[120:121], v12 offset1:32
	v_add_u32_e32 v12, 0x54, v12
	v_lshl_add_u64 v[10:11], v[10:11], 0, v[124:125]
	global_load_dwordx4 v[92:95], v[10:11], off
	ds_read2st64_b32 v[122:123], v12 offset1:32
	s_waitcnt vmcnt(7) lgkmcnt(7)
; __device__ __forceinline__ void adaln_unit(KP p, int u, float* sm, int tid) {
;     ...
;     for (int k = rg; k < DM; k += 21) { const f32x4 w = *(const f32x4*)(W + (size_t)k * 12288); a1 += sm[k] * w; a2 += sm[DM + k] * w; }
;     float* d1 = red + (rg * 2 + 0) * 96 + 4 * c4; d1[0] = a1[0]; d1[1] = a1[1]; d1[2] = a1[2]; d1[3] = a1[3];
;     float* d2 = red + (rg * 2 + 1) * 96 + 4 * c4; d2[0] = a2[0]; d2[1] = a2[1]; d2[2] = a2[2]; d2[3] = a2[3];
	v_pk_fma_f32 v[2:3], v[42:43], v[96:97], v[2:3] op_sel_hi:[1,0,1]
	v_pk_fma_f32 v[0:1], v[40:41], v[96:97], v[0:1] op_sel_hi:[1,0,1]
	v_pk_fma_f32 v[6:7], v[42:43], v[96:97], v[6:7] op_sel:[0,1,0] op_sel_hi:[1,1,1]
	v_pk_fma_f32 v[4:5], v[40:41], v[96:97], v[4:5] op_sel:[0,1,0] op_sel_hi:[1,1,1]
	v_pk_fma_f32 v[2:3], v[46:47], v[98:99], v[2:3] op_sel_hi:[1,0,1]
	v_pk_fma_f32 v[0:1], v[44:45], v[98:99], v[0:1] op_sel_hi:[1,0,1]
	v_pk_fma_f32 v[6:7], v[46:47], v[98:99], v[6:7] op_sel:[0,1,0] op_sel_hi:[1,1,1]
	v_pk_fma_f32 v[4:5], v[44:45], v[98:99], v[4:5] op_sel:[0,1,0] op_sel_hi:[1,1,1]
	v_pk_fma_f32 v[2:3], v[50:51], v[100:101], v[2:3] op_sel_hi:[1,0,1]
	v_pk_fma_f32 v[0:1], v[48:49], v[100:101], v[0:1] op_sel_hi:[1,0,1]
	v_pk_fma_f32 v[6:7], v[50:51], v[100:101], v[6:7] op_sel:[0,1,0] op_sel_hi:[1,1,1]
	v_pk_fma_f32 v[4:5], v[48:49], v[100:101], v[4:5] op_sel:[0,1,0] op_sel_hi:[1,1,1]
	v_pk_fma_f32 v[2:3], v[54:55], v[102:103], v[2:3] op_sel_hi:[1,0,1]
	v_pk_fma_f32 v[0:1], v[52:53], v[102:103], v[0:1] op_sel_hi:[1,0,1]
	v_pk_fma_f32 v[6:7], v[54:55], v[102:103], v[6:7] op_sel:[0,1,0] op_sel_hi:[1,1,1]
	v_pk_fma_f32 v[4:5], v[52:53], v[102:103], v[4:5] op_sel:[0,1,0] op_sel_hi:[1,1,1]
	v_pk_fma_f32 v[2:3], v[58:59], v[104:105], v[2:3] op_sel_hi:[1,0,1]
	v_pk_fma_f32 v[0:1], v[56:57], v[104:105], v[0:1] op_sel_hi:[1,0,1]
	v_pk_fma_f32 v[6:7], v[58:59], v[104:105], v[6:7] op_sel:[0,1,0] op_sel_hi:[1,1,1]
	v_pk_fma_f32 v[4:5], v[56:57], v[104:105], v[4:5] op_sel:[0,1,0] op_sel_hi:[1,1,1]
	v_pk_fma_f32 v[2:3], v[62:63], v[106:107], v[2:3] op_sel_hi:[1,0,1]
	v_pk_fma_f32 v[0:1], v[60:61], v[106:107], v[0:1] op_sel_hi:[1,0,1]
	v_pk_fma_f32 v[6:7], v[62:63], v[106:107], v[6:7] op_sel:[0,1,0] op_sel_hi:[1,1,1]
	v_pk_fma_f32 v[4:5], v[60:61], v[106:107], v[4:5] op_sel:[0,1,0] op_sel_hi:[1,1,1]
	v_pk_fma_f32 v[2:3], v[66:67], v[108:109], v[2:3] op_sel_hi:[1,0,1]
	v_pk_fma_f32 v[0:1], v[64:65], v[108:109], v[0:1] op_sel_hi:[1,0,1]
	v_pk_fma_f32 v[6:7], v[66:67], v[108:109], v[6:7] op_sel:[0,1,0] op_sel_hi:[1,1,1]
	v_pk_fma_f32 v[4:5], v[64:65], v[108:109], v[4:5] op_sel:[0,1,0] op_sel_hi:[1,1,1]
	s_waitcnt vmcnt(0) lgkmcnt(0)
	v_cndmask_b32_e32 v122, 0, v122, vcc
	v_cndmask_b32_e32 v123, 0, v123, vcc
	v_pk_fma_f32 v[2:3], v[70:71], v[110:111], v[2:3] op_sel_hi:[1,0,1]
	v_pk_fma_f32 v[0:1], v[68:69], v[110:111], v[0:1] op_sel_hi:[1,0,1]
	v_pk_fma_f32 v[6:7], v[70:71], v[110:111], v[6:7] op_sel:[0,1,0] op_sel_hi:[1,1,1]
	v_pk_fma_f32 v[4:5], v[68:69], v[110:111], v[4:5] op_sel:[0,1,0] op_sel_hi:[1,1,1]
	v_pk_fma_f32 v[2:3], v[74:75], v[112:113], v[2:3] op_sel_hi:[1,0,1]
	v_pk_fma_f32 v[0:1], v[72:73], v[112:113], v[0:1] op_sel_hi:[1,0,1]
	v_pk_fma_f32 v[6:7], v[74:75], v[112:113], v[6:7] op_sel:[0,1,0] op_sel_hi:[1,1,1]
	v_pk_fma_f32 v[4:5], v[72:73], v[112:113], v[4:5] op_sel:[0,1,0] op_sel_hi:[1,1,1]
	v_pk_fma_f32 v[2:3], v[78:79], v[114:115], v[2:3] op_sel_hi:[1,0,1]
	v_pk_fma_f32 v[0:1], v[76:77], v[114:115], v[0:1] op_sel_hi:[1,0,1]
	v_pk_fma_f32 v[6:7], v[78:79], v[114:115], v[6:7] op_sel:[0,1,0] op_sel_hi:[1,1,1]
	v_pk_fma_f32 v[4:5], v[76:77], v[114:115], v[4:5] op_sel:[0,1,0] op_sel_hi:[1,1,1]
	v_pk_fma_f32 v[2:3], v[82:83], v[116:117], v[2:3] op_sel_hi:[1,0,1]
	v_pk_fma_f32 v[0:1], v[80:81], v[116:117], v[0:1] op_sel_hi:[1,0,1]
	v_pk_fma_f32 v[6:7], v[82:83], v[116:117], v[6:7] op_sel:[0,1,0] op_sel_hi:[1,1,1]
	v_pk_fma_f32 v[4:5], v[80:81], v[116:117], v[4:5] op_sel:[0,1,0] op_sel_hi:[1,1,1]
	v_pk_fma_f32 v[2:3], v[86:87], v[118:119], v[2:3] op_sel_hi:[1,0,1]
	v_pk_fma_f32 v[0:1], v[84:85], v[118:119], v[0:1] op_sel_hi:[1,0,1]
	v_pk_fma_f32 v[6:7], v[86:87], v[118:119], v[6:7] op_sel:[0,1,0] op_sel_hi:[1,1,1]
	v_pk_fma_f32 v[4:5], v[84:85], v[118:119], v[4:5] op_sel:[0,1,0] op_sel_hi:[1,1,1]
	v_pk_fma_f32 v[2:3], v[90:91], v[120:121], v[2:3] op_sel_hi:[1,0,1]
	v_pk_fma_f32 v[0:1], v[88:89], v[120:121], v[0:1] op_sel_hi:[1,0,1]
	v_pk_fma_f32 v[6:7], v[90:91], v[120:121], v[6:7] op_sel:[0,1,0] op_sel_hi:[1,1,1]
	v_pk_fma_f32 v[4:5], v[88:89], v[120:121], v[4:5] op_sel:[0,1,0] op_sel_hi:[1,1,1]
	v_pk_fma_f32 v[2:3], v[94:95], v[122:123], v[2:3] op_sel_hi:[1,0,1]
	v_pk_fma_f32 v[0:1], v[92:93], v[122:123], v[0:1] op_sel_hi:[1,0,1]
	v_pk_fma_f32 v[6:7], v[94:95], v[122:123], v[6:7] op_sel:[0,1,0] op_sel_hi:[1,1,1]
	v_pk_fma_f32 v[4:5], v[92:93], v[122:123], v[4:5] op_sel:[0,1,0] op_sel_hi:[1,1,1]
	s_or_b64 exec, exec, s[18:19]
	ds_write_b128 v25, v[0:3] offset:16384
	ds_write_b128 v25, v[4:7] offset:16768
